# v69 + mixb_fix row: all 12 loads of a row issued up front, counted waits
# baseline (speedup 1.0000x reference)
.LBB0_984:
	s_mov_b64 s[70:71], exec
	s_and_b64 exec, s[70:71], s[38:39]
	v_lshl_add_u64 v[8:9], s[0:1], 0, v[2:3]
	v_add_co_u32_e32 v8, vcc, 0x200000, v8
	s_nop 1
	v_addc_co_u32_e32 v9, vcc, 0, v9, vcc
	global_load_dword v20, v[8:9], off
	global_load_dword v21, v[8:9], off offset:24
	global_load_dword v22, v[8:9], off offset:48
	global_load_dwordx4 v[36:39], v[0:1], off offset:-2048
	s_and_b64 exec, s[70:71], s[44:45]
	v_lshl_add_u64 v[8:9], s[0:1], 0, v[4:5]
	v_add_co_u32_e32 v8, vcc, 0x200000, v8
	s_nop 1
	v_addc_co_u32_e32 v9, vcc, 0, v9, vcc
	global_load_dword v23, v[8:9], off
	global_load_dword v24, v[8:9], off offset:24
	global_load_dword v25, v[8:9], off offset:48
	global_load_dwordx4 v[40:43], v[0:1], off offset:-1024
	s_and_b64 exec, s[70:71], s[50:51]
	v_lshl_add_u64 v[8:9], s[0:1], 0, v[6:7]
	v_add_co_u32_e32 v8, vcc, 0x200000, v8
	s_nop 1
	v_addc_co_u32_e32 v9, vcc, 0, v9, vcc
	global_load_dword v26, v[8:9], off
	global_load_dword v27, v[8:9], off offset:24
	global_load_dword v28, v[8:9], off offset:48
	global_load_dwordx4 v[44:47], v[0:1], off
	s_and_b64 exec, s[70:71], s[38:39]
	s_waitcnt vmcnt(8)
	v_mov_b32_e32 v10, v20
	v_mov_b32_e32 v11, v21
	v_mov_b32_e32 v8, v22
	v_max3_f32 v9, v10, v11, v8
	v_sub_f32_e32 v10, v10, v9
	v_cmp_gt_f32_e32 vcc, s16, v10
	v_sub_f32_e32 v11, v11, v9
	v_sub_f32_e32 v8, v8, v9
	v_cndmask_b32_e32 v12, 0, v241, vcc
	v_add_f32_e32 v10, v10, v12
	v_exp_f32_e32 v10, v10
	v_cndmask_b32_e32 v12, 0, v243, vcc
	v_cmp_gt_f32_e32 vcc, s16, v11
	v_ldexp_f32 v10, v10, v12
	s_nop 0
	v_cndmask_b32_e32 v12, 0, v241, vcc
	v_add_f32_e32 v11, v11, v12
	v_cndmask_b32_e32 v12, 0, v243, vcc
	v_cmp_gt_f32_e32 vcc, s16, v8
	v_exp_f32_e32 v11, v11
	s_nop 0
	v_cndmask_b32_e32 v9, 0, v241, vcc
	v_add_f32_e32 v8, v8, v9
	v_exp_f32_e32 v8, v8
	v_cndmask_b32_e32 v9, 0, v243, vcc
	v_ldexp_f32 v11, v11, v12
	v_ldexp_f32 v8, v8, v9
	v_cndmask_b32_e64 v9, v8, v11, s[42:43]
	v_cndmask_b32_e64 v9, v9, v10, s[40:41]
	v_add_f32_e32 v10, v10, v11
	v_add_f32_e32 v8, v8, v10
	v_div_scale_f32 v10, s[6:7], v8, v8, v9
	v_rcp_f32_e32 v11, v10
	s_nop 0
	v_fma_f32 v12, -v10, v11, 1.0
	v_fmac_f32_e32 v11, v12, v11
	v_div_scale_f32 v12, vcc, v9, v8, v9
	v_mul_f32_e32 v13, v12, v11
	v_fma_f32 v14, -v10, v13, v12
	v_fmac_f32_e32 v13, v14, v11
	v_fma_f32 v10, -v10, v13, v12
	v_div_fmas_f32 v10, v10, v11, v13
	v_div_fixup_f32 v12, v10, v8, v9
	v_mov_b32_e32 v8, v36
	v_mov_b32_e32 v9, v37
	v_mov_b32_e32 v10, v38
	v_mov_b32_e32 v11, v39
	v_lshlrev_b32_e32 v13, 16, v8
	v_and_b32_e32 v8, 0xffff0000, v8
	v_mul_f32_e32 v13, v12, v13
	v_mul_f32_e32 v8, v12, v8
	v_cvt_pk_bf16_f32 v8, v13, v8
	v_lshlrev_b32_e32 v13, 16, v9
	v_and_b32_e32 v9, 0xffff0000, v9
	v_mul_f32_e32 v13, v12, v13
	v_mul_f32_e32 v9, v12, v9
	v_cvt_pk_bf16_f32 v9, v13, v9
	v_lshlrev_b32_e32 v13, 16, v10
	v_and_b32_e32 v10, 0xffff0000, v10
	v_mul_f32_e32 v13, v12, v13
	v_mul_f32_e32 v10, v12, v10
	v_cvt_pk_bf16_f32 v10, v13, v10
	v_lshlrev_b32_e32 v13, 16, v11
	v_and_b32_e32 v11, 0xffff0000, v11
	v_mul_f32_e32 v11, v12, v11
	v_mul_f32_e32 v13, v12, v13
	v_cvt_pk_bf16_f32 v11, v13, v11
	global_store_dwordx4 v[0:1], v[8:11], off offset:-2048
	s_and_b64 exec, s[70:71], s[44:45]
	s_waitcnt vmcnt(5)
	v_mov_b32_e32 v10, v23
	v_mov_b32_e32 v11, v24
	v_mov_b32_e32 v8, v25
	v_max3_f32 v9, v10, v11, v8
	v_sub_f32_e32 v10, v10, v9
	v_cmp_gt_f32_e32 vcc, s16, v10
	v_sub_f32_e32 v11, v11, v9
	v_sub_f32_e32 v8, v8, v9
	v_cndmask_b32_e32 v12, 0, v241, vcc
	v_add_f32_e32 v10, v10, v12
	v_exp_f32_e32 v10, v10
	v_cndmask_b32_e32 v12, 0, v243, vcc
	v_cmp_gt_f32_e32 vcc, s16, v11
	v_ldexp_f32 v10, v10, v12
	s_nop 0
	v_cndmask_b32_e32 v12, 0, v241, vcc
	v_add_f32_e32 v11, v11, v12
	v_cndmask_b32_e32 v12, 0, v243, vcc
	v_cmp_gt_f32_e32 vcc, s16, v8
	v_exp_f32_e32 v11, v11
	s_nop 0
	v_cndmask_b32_e32 v9, 0, v241, vcc
	v_add_f32_e32 v8, v8, v9
	v_exp_f32_e32 v8, v8
	v_cndmask_b32_e32 v9, 0, v243, vcc
	v_ldexp_f32 v11, v11, v12
	v_ldexp_f32 v8, v8, v9
	v_cndmask_b32_e64 v9, v8, v11, s[48:49]
	v_cndmask_b32_e64 v9, v9, v10, s[46:47]
	v_add_f32_e32 v10, v10, v11
	v_add_f32_e32 v8, v8, v10
	v_div_scale_f32 v10, s[6:7], v8, v8, v9
	v_rcp_f32_e32 v11, v10
	s_nop 0
	v_fma_f32 v12, -v10, v11, 1.0
	v_fmac_f32_e32 v11, v12, v11
	v_div_scale_f32 v12, vcc, v9, v8, v9
	v_mul_f32_e32 v13, v12, v11
	v_fma_f32 v14, -v10, v13, v12
	v_fmac_f32_e32 v13, v14, v11
	v_fma_f32 v10, -v10, v13, v12
	v_div_fmas_f32 v10, v10, v11, v13
	v_div_fixup_f32 v12, v10, v8, v9
	v_mov_b32_e32 v8, v40
	v_mov_b32_e32 v9, v41
	v_mov_b32_e32 v10, v42
	v_mov_b32_e32 v11, v43
	v_lshlrev_b32_e32 v13, 16, v8
	v_and_b32_e32 v8, 0xffff0000, v8
	v_mul_f32_e32 v13, v12, v13
	v_mul_f32_e32 v8, v12, v8
	v_cvt_pk_bf16_f32 v8, v13, v8
	v_lshlrev_b32_e32 v13, 16, v9
	v_and_b32_e32 v9, 0xffff0000, v9
	v_mul_f32_e32 v13, v12, v13
	v_mul_f32_e32 v9, v12, v9
	v_cvt_pk_bf16_f32 v9, v13, v9
	v_lshlrev_b32_e32 v13, 16, v10
	v_and_b32_e32 v10, 0xffff0000, v10
	v_mul_f32_e32 v13, v12, v13
	v_mul_f32_e32 v10, v12, v10
	v_cvt_pk_bf16_f32 v10, v13, v10
	v_lshlrev_b32_e32 v13, 16, v11
	v_and_b32_e32 v11, 0xffff0000, v11
	v_mul_f32_e32 v11, v12, v11
	v_mul_f32_e32 v13, v12, v13
	v_cvt_pk_bf16_f32 v11, v13, v11
	global_store_dwordx4 v[0:1], v[8:11], off offset:-1024
	s_and_b64 exec, s[70:71], s[50:51]
	s_waitcnt vmcnt(2)
	v_mov_b32_e32 v10, v26
	v_mov_b32_e32 v11, v27
	v_mov_b32_e32 v8, v28
	v_max3_f32 v9, v10, v11, v8
	v_sub_f32_e32 v10, v10, v9
	v_cmp_gt_f32_e32 vcc, s16, v10
	v_sub_f32_e32 v11, v11, v9
	v_sub_f32_e32 v8, v8, v9
	v_cndmask_b32_e32 v12, 0, v241, vcc
	v_add_f32_e32 v10, v10, v12
	v_exp_f32_e32 v10, v10
	v_cndmask_b32_e32 v12, 0, v243, vcc
	v_cmp_gt_f32_e32 vcc, s16, v11
	v_ldexp_f32 v10, v10, v12
	s_nop 0
	v_cndmask_b32_e32 v12, 0, v241, vcc
	v_add_f32_e32 v11, v11, v12
	v_cndmask_b32_e32 v12, 0, v243, vcc
	v_cmp_gt_f32_e32 vcc, s16, v8
	v_exp_f32_e32 v11, v11
	s_nop 0
	v_cndmask_b32_e32 v9, 0, v241, vcc
	v_add_f32_e32 v8, v8, v9
	v_exp_f32_e32 v8, v8
	v_cndmask_b32_e32 v9, 0, v243, vcc
	v_ldexp_f32 v11, v11, v12
	v_ldexp_f32 v8, v8, v9
	v_cndmask_b32_e64 v9, v8, v11, s[54:55]
	v_cndmask_b32_e64 v9, v9, v10, s[52:53]
	v_add_f32_e32 v10, v10, v11
	v_add_f32_e32 v8, v8, v10
	v_div_scale_f32 v10, s[6:7], v8, v8, v9
	v_rcp_f32_e32 v11, v10
	s_nop 0
	v_fma_f32 v12, -v10, v11, 1.0
	v_fmac_f32_e32 v11, v12, v11
	v_div_scale_f32 v12, vcc, v9, v8, v9
	v_mul_f32_e32 v13, v12, v11
	v_fma_f32 v14, -v10, v13, v12
	v_fmac_f32_e32 v13, v14, v11
	v_fma_f32 v10, -v10, v13, v12
	v_div_fmas_f32 v10, v10, v11, v13
	v_div_fixup_f32 v12, v10, v8, v9
	v_mov_b32_e32 v8, v44
	v_mov_b32_e32 v9, v45
	v_mov_b32_e32 v10, v46
	v_mov_b32_e32 v11, v47
	v_lshlrev_b32_e32 v13, 16, v8
	v_and_b32_e32 v8, 0xffff0000, v8
	v_mul_f32_e32 v13, v12, v13
	v_mul_f32_e32 v8, v12, v8
	v_cvt_pk_bf16_f32 v8, v13, v8
	v_lshlrev_b32_e32 v13, 16, v9
	v_and_b32_e32 v9, 0xffff0000, v9
	v_mul_f32_e32 v13, v12, v13
	v_mul_f32_e32 v9, v12, v9
	v_cvt_pk_bf16_f32 v9, v13, v9
	v_lshlrev_b32_e32 v13, 16, v10
	v_and_b32_e32 v10, 0xffff0000, v10
	v_mul_f32_e32 v13, v12, v13
	v_mul_f32_e32 v10, v12, v10
	v_cvt_pk_bf16_f32 v10, v13, v10
	v_lshlrev_b32_e32 v13, 16, v11
	v_and_b32_e32 v11, 0xffff0000, v11
	v_mul_f32_e32 v11, v12, v11
	v_mul_f32_e32 v13, v12, v13
	v_cvt_pk_bf16_f32 v11, v13, v11
	global_store_dwordx4 v[0:1], v[8:11], off
	s_branch .LBB0_983
